# v035: v032 + sample-group attention Q.K^T: counted vmcnt waits (second key block's loads stay in flight during the first block's MFMAs)
# baseline (speedup 1.0000x reference)
.LBB0_50:
	s_ashr_i32 s4, s25, 2
	s_ashr_i32 s5, s4, 31
	s_lshl_b64 s[16:17], s[4:5], 18
	s_add_u32 s16, s16, s10
	s_addc_u32 s17, s17, s11
	s_lshl_b32 s26, s4, 3
	v_mov_b32_e32 v101, v214
	s_addk_i32 s26, 0x4000
	s_and_b32 s27, s23, 0x300
	v_and_or_b32 v0, v101, 7, s26
	v_ashrrev_i32_e32 v1, 31, v0
	s_mov_b64 s[4:5], s[42:43]
	v_lshlrev_b64 v[0:1], 11, v[0:1]
	s_lshl_b32 s82, s27, 1
	v_lshl_add_u64 v[0:1], s[4:5], 0, v[0:1]
	v_lshl_add_u64 v[0:1], v[0:1], 0, s[82:83]
	v_and_b32_e32 v192, 48, v101
	v_lshl_add_u64 v[0:1], v[0:1], 0, v[192:193]
	s_lshl_b64 s[16:17], s[16:17], 2
	v_add_co_u32_e32 v2, vcc, s31, v0
	v_ashrrev_i32_e32 v124, 6, v101
	s_add_u32 s4, s58, s16
	v_and_b32_e32 v122, 15, v101
	v_addc_co_u32_e32 v3, vcc, 0, v1, vcc
	s_addc_u32 s5, s59, s17
	s_lshl_b32 s27, s27, 2
	v_lshlrev_b32_e32 v100, 5, v124
	v_bfe_u32 v123, v101, 4, 2
	global_load_dwordx4 v[64:67], v[2:3], off
	s_add_u32 s4, s4, s27
	v_or_b32_e32 v2, v100, v122
	s_addc_u32 s5, s5, 0
	v_lshlrev_b32_e32 v192, 5, v123
	v_ashrrev_i32_e32 v3, 31, v2
	v_lshl_add_u64 v[4:5], s[4:5], 0, v[192:193]
	v_lshlrev_b64 v[6:7], 12, v[2:3]
	v_lshl_add_u64 v[6:7], v[4:5], 0, v[6:7]
	global_load_dwordx4 v[68:71], v[6:7], off
	global_load_dwordx4 v[72:75], v[6:7], off offset:16
	global_load_dwordx4 v[76:79], v[6:7], off offset:128
	global_load_dwordx4 v[80:83], v[6:7], off offset:144
	s_mov_b64 s[4:5], 0xfc00000
	v_lshl_add_u64 v[0:1], v[0:1], 0, s[4:5]
	global_load_dwordx4 v[84:87], v[0:1], off offset:64
	global_load_dwordx4 v[88:91], v[6:7], off offset:256
	global_load_dwordx4 v[92:95], v[6:7], off offset:272
	global_load_dwordx4 v[96:99], v[0:1], off offset:128
	global_load_dwordx4 v[102:105], v[6:7], off offset:384
	global_load_dwordx4 v[106:109], v[6:7], off offset:400
	global_load_dwordx4 v[110:113], v[0:1], off offset:192
	global_load_dwordx4 v[114:117], v[6:7], off offset:512
	global_load_dwordx4 v[118:121], v[6:7], off offset:528
	s_waitcnt lgkmcnt(0)
	global_load_dwordx4 v[126:129], v[0:1], off offset:256
	global_load_dwordx4 v[130:133], v[6:7], off offset:640
	global_load_dwordx4 v[134:137], v[6:7], off offset:656
	global_load_dwordx4 v[138:141], v[0:1], off offset:320
	global_load_dwordx4 v[142:145], v[6:7], off offset:784
	global_load_dwordx4 v[146:149], v[6:7], off offset:768
	global_load_dwordx4 v[150:153], v[0:1], off offset:384
	global_load_dwordx4 v[154:157], v[0:1], off offset:448
	v_or_b32_e32 v2, 16, v2
	v_ashrrev_i32_e32 v3, 31, v2
	v_lshlrev_b64 v[2:3], 12, v[2:3]
	v_lshl_add_u64 v[4:5], v[4:5], 0, v[2:3]
	global_load_dwordx4 v[158:161], v[6:7], off offset:912
	global_load_dwordx4 v[162:165], v[6:7], off offset:896
	global_load_dwordx4 v[56:59], v[4:5], off offset:16
	global_load_dwordx4 v[60:63], v[4:5], off
	global_load_dwordx4 v[48:51], v[4:5], off offset:144
	global_load_dwordx4 v[52:55], v[4:5], off offset:128
	global_load_dwordx4 v[40:43], v[4:5], off offset:272
	global_load_dwordx4 v[44:47], v[4:5], off offset:256
	global_load_dwordx4 v[32:35], v[4:5], off offset:400
	global_load_dwordx4 v[36:39], v[4:5], off offset:384
	global_load_dwordx4 v[24:27], v[4:5], off offset:528
	global_load_dwordx4 v[28:31], v[4:5], off offset:512
	global_load_dwordx4 v[16:19], v[4:5], off offset:656
	global_load_dwordx4 v[20:23], v[4:5], off offset:640
	global_load_dwordx4 v[8:11], v[4:5], off offset:784
	global_load_dwordx4 v[12:15], v[4:5], off offset:768
	global_load_dwordx4 v[0:3], v[4:5], off offset:912
	s_nop 0
	global_load_dwordx4 v[4:7], v[4:5], off offset:896
	v_cmp_lt_u32_e64 s[4:5], 7, v122
	v_lshl_add_u32 v125, v122, 2, 0
	v_lshl_or_b32 v123, v123, 2, v100
	v_cmp_gt_u32_e32 vcc, 8, v122
	s_waitcnt vmcnt(16) lgkmcnt(0)
	v_cndmask_b32_e64 v67, v67, 0, s[4:5]
	v_cndmask_b32_e64 v66, v66, 0, s[4:5]
	v_cndmask_b32_e64 v65, v65, 0, s[4:5]
	v_cndmask_b32_e64 v64, v64, 0, s[4:5]
	v_cvt_pk_bf16_f32 v68, v68, v69
	v_cvt_pk_bf16_f32 v69, v70, v71
	v_cvt_pk_bf16_f32 v70, v72, v73
	v_cvt_pk_bf16_f32 v71, v74, v75
	v_cvt_pk_bf16_f32 v72, v76, v77
	v_cvt_pk_bf16_f32 v73, v78, v79
	v_cvt_pk_bf16_f32 v74, v80, v81
	v_cvt_pk_bf16_f32 v75, v82, v83
	v_mfma_f32_16x16x32_bf16 v[76:79], v[68:71], v[64:67], 0
	v_cndmask_b32_e64 v71, v87, 0, s[4:5]
	v_cndmask_b32_e64 v70, v86, 0, s[4:5]
	v_cndmask_b32_e64 v69, v85, 0, s[4:5]
	v_cndmask_b32_e64 v68, v84, 0, s[4:5]
	v_cvt_pk_bf16_f32 v80, v88, v89
	v_cvt_pk_bf16_f32 v81, v90, v91
	v_cvt_pk_bf16_f32 v82, v92, v93
	v_cvt_pk_bf16_f32 v83, v94, v95
	v_mfma_f32_16x16x32_bf16 v[76:79], v[72:75], v[68:71], v[76:79]
	v_cndmask_b32_e64 v75, v99, 0, s[4:5]
	v_cndmask_b32_e64 v74, v98, 0, s[4:5]
	v_cndmask_b32_e64 v73, v97, 0, s[4:5]
	v_cndmask_b32_e64 v72, v96, 0, s[4:5]
	v_cvt_pk_bf16_f32 v84, v102, v103
	v_cvt_pk_bf16_f32 v85, v104, v105
	v_cvt_pk_bf16_f32 v86, v106, v107
	v_cvt_pk_bf16_f32 v87, v108, v109
	v_mfma_f32_16x16x32_bf16 v[80:83], v[80:83], v[72:75], v[76:79]
	v_cvt_pk_bf16_f32 v88, v114, v115
	v_cvt_pk_bf16_f32 v89, v116, v117
	v_cvt_pk_bf16_f32 v90, v118, v119
	v_cndmask_b32_e64 v79, v113, 0, s[4:5]
	v_cndmask_b32_e64 v78, v112, 0, s[4:5]
	v_cndmask_b32_e64 v77, v111, 0, s[4:5]
	v_cndmask_b32_e64 v76, v110, 0, s[4:5]
	v_cvt_pk_bf16_f32 v91, v120, v121
	v_cvt_pk_bf16_f32 v92, v130, v131
	v_mfma_f32_16x16x32_bf16 v[84:87], v[84:87], v[76:79], v[80:83]
	v_cvt_pk_bf16_f32 v93, v132, v133
	v_cvt_pk_bf16_f32 v94, v134, v135
	v_cvt_pk_bf16_f32 v95, v136, v137
	v_cndmask_b32_e64 v83, v129, 0, s[4:5]
	v_cndmask_b32_e64 v82, v128, 0, s[4:5]
	v_cndmask_b32_e64 v81, v127, 0, s[4:5]
	v_cndmask_b32_e64 v80, v126, 0, s[4:5]
	v_cvt_pk_bf16_f32 v96, v146, v147
	v_cvt_pk_bf16_f32 v97, v148, v149
	v_mfma_f32_16x16x32_bf16 v[88:91], v[88:91], v[80:83], v[84:87]
	v_cvt_pk_bf16_f32 v98, v142, v143
	v_cvt_pk_bf16_f32 v99, v144, v145
	v_cvt_pk_bf16_f32 v102, v162, v163
	v_cndmask_b32_e64 v87, v141, 0, s[4:5]
	v_cndmask_b32_e64 v86, v140, 0, s[4:5]
	v_cndmask_b32_e64 v85, v139, 0, s[4:5]
	v_cndmask_b32_e64 v84, v138, 0, s[4:5]
	v_cvt_pk_bf16_f32 v103, v164, v165
	v_cvt_pk_bf16_f32 v104, v158, v159
	v_mfma_f32_16x16x32_bf16 v[92:95], v[92:95], v[84:87], v[88:91]
	v_cvt_pk_bf16_f32 v105, v160, v161
	s_nop 1
	v_cndmask_b32_e64 v91, v153, 0, s[4:5]
	v_cndmask_b32_e64 v90, v152, 0, s[4:5]
	v_cndmask_b32_e64 v89, v151, 0, s[4:5]
	v_cndmask_b32_e64 v88, v150, 0, s[4:5]
	s_nop 1
	v_mfma_f32_16x16x32_bf16 v[96:99], v[96:99], v[88:91], v[92:95]
	s_nop 2
	v_cndmask_b32_e64 v95, v157, 0, s[4:5]
	v_cndmask_b32_e64 v94, v156, 0, s[4:5]
	v_cndmask_b32_e64 v93, v155, 0, s[4:5]
	v_cndmask_b32_e64 v92, v154, 0, s[4:5]
	s_nop 1
	v_mfma_f32_16x16x32_bf16 v[96:99], v[102:105], v[92:95], v[96:99]
	v_lshl_add_u32 v102, v123, 5, v125
	s_and_saveexec_b64 s[4:5], vcc
	s_cbranch_execz .LBB0_52
	s_nop 4
	ds_write2_b32 v102, v96, v97 offset1:8
	ds_write2_b32 v102, v98, v99 offset0:16 offset1:24
.LBB0_52:
	s_or_b64 exec, exec, s[4:5]
	s_waitcnt vmcnt(14)
	v_cvt_pk_bf16_f32 v60, v60, v61
	v_cvt_pk_bf16_f32 v61, v62, v63
	v_cvt_pk_bf16_f32 v62, v56, v57
	v_cvt_pk_bf16_f32 v63, v58, v59
	s_waitcnt vmcnt(12)
	v_cvt_pk_bf16_f32 v52, v52, v53
	v_cvt_pk_bf16_f32 v53, v54, v55
	v_cvt_pk_bf16_f32 v54, v48, v49
	v_cvt_pk_bf16_f32 v55, v50, v51
	v_mfma_f32_16x16x32_bf16 v[56:59], v[60:63], v[64:67], 0
	s_waitcnt vmcnt(10)
	v_cvt_pk_bf16_f32 v44, v44, v45
	v_cvt_pk_bf16_f32 v45, v46, v47
	v_cvt_pk_bf16_f32 v46, v40, v41
	v_cvt_pk_bf16_f32 v47, v42, v43
	v_mfma_f32_16x16x32_bf16 v[48:51], v[52:55], v[68:71], v[56:59]
	s_waitcnt vmcnt(8)
	v_cvt_pk_bf16_f32 v36, v36, v37
	v_cvt_pk_bf16_f32 v37, v38, v39
	v_cvt_pk_bf16_f32 v38, v32, v33
	v_cvt_pk_bf16_f32 v39, v34, v35
	v_mfma_f32_16x16x32_bf16 v[40:43], v[44:47], v[72:75], v[48:51]
	s_waitcnt vmcnt(6)
	v_cvt_pk_bf16_f32 v28, v28, v29
	v_cvt_pk_bf16_f32 v29, v30, v31
	v_cvt_pk_bf16_f32 v30, v24, v25
	v_cvt_pk_bf16_f32 v31, v26, v27
	v_mfma_f32_16x16x32_bf16 v[32:35], v[36:39], v[76:79], v[40:43]
	s_waitcnt vmcnt(4)
	v_cvt_pk_bf16_f32 v20, v20, v21
	v_cvt_pk_bf16_f32 v21, v22, v23
	v_cvt_pk_bf16_f32 v22, v16, v17
	v_cvt_pk_bf16_f32 v23, v18, v19
	v_mfma_f32_16x16x32_bf16 v[24:27], v[28:31], v[80:83], v[32:35]
	s_waitcnt vmcnt(2)
	v_cvt_pk_bf16_f32 v12, v12, v13
	v_cvt_pk_bf16_f32 v13, v14, v15
	v_cvt_pk_bf16_f32 v14, v8, v9
	v_cvt_pk_bf16_f32 v15, v10, v11
	v_mfma_f32_16x16x32_bf16 v[16:19], v[20:23], v[84:87], v[24:27]
	s_waitcnt vmcnt(0)
	v_cvt_pk_bf16_f32 v4, v4, v5
	v_cvt_pk_bf16_f32 v5, v6, v7
	v_cvt_pk_bf16_f32 v6, v0, v1
	v_cvt_pk_bf16_f32 v7, v2, v3
	v_mfma_f32_16x16x32_bf16 v[8:11], v[12:15], v[88:91], v[16:19]
	s_nop 0
	v_mfma_f32_16x16x32_bf16 v[0:3], v[4:7], v[92:95], v[8:11]
	s_and_saveexec_b64 s[4:5], vcc
	s_cbranch_execz .LBB0_49
	s_nop 5
	ds_write2_b32 v102, v0, v1 offset0:128 offset1:136
	ds_write2_b32 v102, v2, v3 offset0:144 offset1:152
	s_branch .LBB0_49
